# counted waits for the hoisted P4/P9 shift/scale loads (row + chunk 0 first, later chunks stay in flight) on v227
# baseline (speedup 1.0000x reference)
.LBB0_439:
	global_load_dwordx4 v[36:39], v[34:35], off nt
	global_load_dwordx4 v[40:43], v[34:35], off offset:1024 nt
	global_load_dwordx4 v[56:59], v[34:35], off offset:2048 nt
	global_load_dwordx4 v[60:63], v[34:35], off offset:3072 nt
	s_ashr_i32 s6, s12, 12
	s_mul_hi_i32 s7, s6, 0x12000
	s_mul_i32 s6, s6, 0x12000
	s_add_u32 s8, s50, s6
	s_addc_u32 s9, s51, s7
	s_add_u32 s6, s8, 0x6000
	s_addc_u32 s7, s9, 0
	s_add_u32 s8, s8, 0x8000
	s_addc_u32 s9, s9, 0
	global_load_dwordx4 v[64:67], v51, s[6:7] offset:16
	global_load_dwordx4 v[68:71], v51, s[6:7]
	global_load_dwordx4 v[72:75], v51, s[8:9] offset:16
	global_load_dwordx4 v[76:79], v51, s[8:9]
	global_load_dwordx4 v[130:133], v52, s[8:9]
	global_load_dwordx4 v[134:137], v52, s[8:9] offset:16
	global_load_dwordx4 v[138:141], v52, s[6:7]
	global_load_dwordx4 v[142:145], v52, s[6:7] offset:16
	global_load_dwordx4 v[146:149], v53, s[8:9]
	global_load_dwordx4 v[150:153], v53, s[8:9] offset:16
	global_load_dwordx4 v[154:157], v53, s[6:7]
	global_load_dwordx4 v[158:161], v53, s[6:7] offset:16
	global_load_dwordx4 v[162:165], v54, s[8:9]
	global_load_dwordx4 v[166:169], v54, s[8:9] offset:16
	global_load_dwordx4 v[170:173], v54, s[6:7]
	global_load_dwordx4 v[174:177], v54, s[6:7] offset:16
	v_add_co_u32_e32 v80, vcc, s10, v34
	s_add_i32 s12, s12, s101
	s_nop 0
	v_addc_co_u32_e32 v81, vcc, -1, v35, vcc
	s_cmp_lt_i32 s12, s100
	s_waitcnt vmcnt(12)
	v_cvt_f32_f16_sdwa v83, v36 dst_sel:DWORD dst_unused:UNUSED_PAD src0_sel:WORD_1
	v_cvt_f32_f16_sdwa v85, v37 dst_sel:DWORD dst_unused:UNUSED_PAD src0_sel:WORD_1
	v_cvt_f32_f16_sdwa v87, v38 dst_sel:DWORD dst_unused:UNUSED_PAD src0_sel:WORD_1
	v_cvt_f32_f16_sdwa v89, v39 dst_sel:DWORD dst_unused:UNUSED_PAD src0_sel:WORD_1
	v_cvt_f32_f16_e32 v82, v36
	v_cvt_f32_f16_e32 v84, v37
	v_cvt_f32_f16_e32 v86, v38
	v_cvt_f32_f16_e32 v88, v39
	v_cvt_f32_f16_sdwa v91, v40 dst_sel:DWORD dst_unused:UNUSED_PAD src0_sel:WORD_1
	v_cvt_f32_f16_sdwa v93, v41 dst_sel:DWORD dst_unused:UNUSED_PAD src0_sel:WORD_1
	v_cvt_f32_f16_e32 v90, v40
	v_cvt_f32_f16_e32 v92, v41
	v_cvt_f32_f16_e32 v94, v42
	v_cvt_f32_f16_e32 v96, v43
	v_cvt_f32_f16_sdwa v95, v42 dst_sel:DWORD dst_unused:UNUSED_PAD src0_sel:WORD_1
	v_cvt_f32_f16_sdwa v97, v43 dst_sel:DWORD dst_unused:UNUSED_PAD src0_sel:WORD_1
	v_cvt_f32_f16_sdwa v99, v56 dst_sel:DWORD dst_unused:UNUSED_PAD src0_sel:WORD_1
	v_cvt_f32_f16_e32 v98, v56
	v_cvt_f32_f16_sdwa v101, v57 dst_sel:DWORD dst_unused:UNUSED_PAD src0_sel:WORD_1
	v_cvt_f32_f16_e32 v100, v57
	v_cvt_f32_f16_sdwa v103, v58 dst_sel:DWORD dst_unused:UNUSED_PAD src0_sel:WORD_1
	v_cvt_f32_f16_e32 v102, v58
	v_cvt_f32_f16_sdwa v105, v59 dst_sel:DWORD dst_unused:UNUSED_PAD src0_sel:WORD_1
	v_cvt_f32_f16_e32 v104, v59
	v_cvt_f32_f16_sdwa v39, v62 dst_sel:DWORD dst_unused:UNUSED_PAD src0_sel:WORD_1
	v_cvt_f32_f16_e32 v38, v62
	v_cvt_f32_f16_sdwa v43, v63 dst_sel:DWORD dst_unused:UNUSED_PAD src0_sel:WORD_1
	v_cvt_f32_f16_e32 v42, v63
	v_mov_b32_e32 v58, v83
	v_mov_b32_e32 v59, v87
	v_mov_b32_e32 v62, v85
	v_mov_b32_e32 v63, v89
	v_cvt_f32_f16_sdwa v37, v60 dst_sel:DWORD dst_unused:UNUSED_PAD src0_sel:WORD_1
	v_cvt_f32_f16_e32 v36, v60
	v_cvt_f32_f16_sdwa v41, v61 dst_sel:DWORD dst_unused:UNUSED_PAD src0_sel:WORD_1
	v_cvt_f32_f16_e32 v40, v61
	v_mov_b32_e32 v56, v82
	v_mov_b32_e32 v57, v86
	v_mov_b32_e32 v60, v84
	v_mov_b32_e32 v61, v88
	v_mov_b32_e32 v108, v91
	v_mov_b32_e32 v109, v93
	v_pk_mul_f32 v[58:59], v[58:59], v[58:59]
	v_pk_mul_f32 v[62:63], v[62:63], v[62:63]
	v_mov_b32_e32 v106, v90
	v_mov_b32_e32 v107, v92
	v_pk_mul_f32 v[108:109], v[108:109], v[108:109]
	v_pk_fma_f32 v[56:57], v[56:57], v[56:57], v[58:59]
	v_pk_fma_f32 v[58:59], v[60:61], v[60:61], v[62:63]
	v_mul_f32_e32 v110, v94, v94
	v_mul_f32_e32 v112, v96, v96
	v_pk_fma_f32 v[60:61], v[106:107], v[106:107], v[108:109]
	v_pk_add_f32 v[56:57], v[56:57], v[58:59]
	v_pk_mul_f32 v[114:115], v[98:99], v[98:99]
	v_pk_mul_f32 v[116:117], v[100:101], v[100:101]
	v_pk_fma_f32 v[110:111], v[94:95], v[94:95], v[110:111] op_sel_hi:[1,1,0]
	v_pk_fma_f32 v[112:113], v[96:97], v[96:97], v[112:113] op_sel_hi:[1,1,0]
	v_pk_add_f32 v[58:59], v[60:61], v[60:61] op_sel_hi:[0,1]
	v_pk_add_f32 v[56:57], v[56:57], v[56:57] op_sel_hi:[0,1]
	v_mov_b32_e32 v120, v103
	v_mov_b32_e32 v121, v105
	v_mov_b32_e32 v110, v114
	v_mov_b32_e32 v112, v115
	v_mov_b32_e32 v58, v117
	v_mov_b32_e32 v56, v116
	v_mov_b32_e32 v118, v102
	v_mov_b32_e32 v119, v104
	v_pk_mul_f32 v[120:121], v[120:121], v[120:121]
	v_pk_add_f32 v[60:61], v[110:111], v[112:113]
	v_pk_add_f32 v[56:57], v[56:57], v[58:59]
	v_mul_f32_e32 v122, v36, v36
	v_mul_f32_e32 v124, v40, v40
	v_pk_fma_f32 v[62:63], v[118:119], v[118:119], v[120:121]
	v_pk_add_f32 v[56:57], v[60:61], v[56:57]
	v_pk_mul_f32 v[126:127], v[38:39], v[38:39]
	v_pk_mul_f32 v[128:129], v[42:43], v[42:43]
	v_pk_fma_f32 v[122:123], v[36:37], v[36:37], v[122:123] op_sel_hi:[1,1,0]
	v_pk_fma_f32 v[124:125], v[40:41], v[40:41], v[124:125] op_sel_hi:[1,1,0]
	v_pk_add_f32 v[62:63], v[62:63], v[62:63] op_sel_hi:[0,1]
	v_pk_add_f32 v[56:57], v[56:57], v[56:57] op_sel_hi:[0,1]
	v_mov_b32_e32 v122, v126
	v_mov_b32_e32 v124, v127
	v_mov_b32_e32 v62, v128
	v_mov_b32_e32 v56, v129
	v_pk_add_f32 v[106:107], v[122:123], v[124:125]
	v_pk_add_f32 v[56:57], v[62:63], v[56:57]
	v_pk_add_f32 v[78:79], v[78:79], 1.0 op_sel_hi:[1,0]
	v_pk_add_f32 v[56:57], v[106:107], v[56:57]
	v_pk_add_f32 v[76:77], v[76:77], 1.0 op_sel_hi:[1,0]
	v_add_f32_e32 v55, v56, v57
	ds_bpermute_b32 v56, v44, v55
	v_pk_add_f32 v[74:75], v[74:75], 1.0 op_sel_hi:[1,0]
	v_pk_add_f32 v[72:73], v[72:73], 1.0 op_sel_hi:[1,0]
	s_waitcnt lgkmcnt(0)
	v_add_f32_e32 v55, v55, v56
	ds_bpermute_b32 v56, v45, v55
	s_waitcnt lgkmcnt(0)
	v_add_f32_e32 v55, v55, v56
	ds_bpermute_b32 v56, v46, v55
	s_waitcnt lgkmcnt(0)
	v_add_f32_e32 v55, v55, v56
	ds_bpermute_b32 v56, v47, v55
	s_waitcnt lgkmcnt(0)
	v_add_f32_e32 v55, v55, v56
	ds_bpermute_b32 v56, v48, v55
	s_waitcnt lgkmcnt(0)
	v_add_f32_e32 v55, v55, v56
	ds_bpermute_b32 v56, v49, v55
	s_waitcnt lgkmcnt(0)
	v_add_f32_e32 v55, v55, v56
	v_fmamk_f32 v55, v55, 0x3a000000, v50
	v_rsq_f32_e32 v106, v55
	s_nop 0
	v_pk_mul_f32 v[56:57], v[84:85], v[106:107] op_sel_hi:[1,0]
	v_pk_mul_f32 v[58:59], v[82:83], v[106:107] op_sel_hi:[1,0]
	v_pk_mul_f32 v[60:61], v[88:89], v[106:107] op_sel_hi:[1,0]
	v_pk_mul_f32 v[62:63], v[86:87], v[106:107] op_sel_hi:[1,0]
	v_pk_mul_f32 v[58:59], v[6:7], v[58:59]
	v_pk_mul_f32 v[56:57], v[8:9], v[56:57]
	v_pk_mul_f32 v[62:63], v[2:3], v[62:63]
	v_pk_mul_f32 v[60:61], v[4:5], v[60:61]
	v_pk_fma_f32 v[70:71], v[78:79], v[56:57], v[70:71]
	v_pk_fma_f32 v[56:57], v[76:77], v[58:59], v[68:69]
	v_pk_fma_f32 v[60:61], v[74:75], v[60:61], v[66:67]
	v_pk_fma_f32 v[58:59], v[72:73], v[62:63], v[64:65]
	v_cvt_pk_bf16_f32 v56, v56, v57
	v_cvt_pk_bf16_f32 v57, v70, v71
	v_cvt_pk_bf16_f32 v58, v58, v59
	v_cvt_pk_bf16_f32 v59, v60, v61
	global_store_dwordx4 v[80:81], v[56:59], off sc1
	v_pk_mul_f32 v[74:75], v[92:93], v[106:107] op_sel_hi:[1,0]
	v_pk_mul_f32 v[76:77], v[90:91], v[106:107] op_sel_hi:[1,0]
	v_pk_mul_f32 v[78:79], v[96:97], v[106:107] op_sel_hi:[1,0]
	v_pk_mul_f32 v[80:81], v[94:95], v[106:107] op_sel_hi:[1,0]
	v_pk_mul_f32 v[76:77], v[14:15], v[76:77]
	v_pk_mul_f32 v[74:75], v[16:17], v[74:75]
	v_pk_mul_f32 v[80:81], v[10:11], v[80:81]
	v_pk_mul_f32 v[78:79], v[12:13], v[78:79]
	v_add_co_u32_e32 v72, vcc, s11, v34
	v_pk_mul_f32 v[40:41], v[40:41], v[106:107] op_sel_hi:[1,0]
	s_nop 0
	v_addc_co_u32_e32 v73, vcc, -1, v35, vcc
	v_pk_mul_f32 v[36:37], v[36:37], v[106:107] op_sel_hi:[1,0]
	v_pk_mul_f32 v[42:43], v[42:43], v[106:107] op_sel_hi:[1,0]
	v_pk_mul_f32 v[38:39], v[38:39], v[106:107] op_sel_hi:[1,0]
	v_pk_mul_f32 v[36:37], v[30:31], v[36:37]
	v_pk_mul_f32 v[40:41], v[32:33], v[40:41]
	v_pk_mul_f32 v[38:39], v[26:27], v[38:39]
	v_pk_mul_f32 v[42:43], v[28:29], v[42:43]
	v_lshl_add_u64 v[34:35], v[34:35], 0, s[0:1]
	s_waitcnt vmcnt(9)
	v_pk_add_f32 v[58:59], v[132:133], 1.0 op_sel_hi:[1,0]
	v_pk_add_f32 v[56:57], v[130:131], 1.0 op_sel_hi:[1,0]
	v_pk_add_f32 v[62:63], v[136:137], 1.0 op_sel_hi:[1,0]
	v_pk_add_f32 v[60:61], v[134:135], 1.0 op_sel_hi:[1,0]
	v_pk_fma_f32 v[58:59], v[58:59], v[74:75], v[140:141]
	v_pk_fma_f32 v[56:57], v[56:57], v[76:77], v[138:139]
	v_pk_fma_f32 v[62:63], v[62:63], v[78:79], v[144:145]
	v_pk_fma_f32 v[60:61], v[60:61], v[80:81], v[142:143]
	v_cvt_pk_bf16_f32 v56, v56, v57
	v_cvt_pk_bf16_f32 v57, v58, v59
	v_cvt_pk_bf16_f32 v58, v60, v61
	v_cvt_pk_bf16_f32 v59, v62, v63
	global_store_dwordx4 v[72:73], v[56:59], off offset:-3072 sc1
	v_pk_mul_f32 v[74:75], v[100:101], v[106:107] op_sel_hi:[1,0]
	v_pk_mul_f32 v[76:77], v[98:99], v[106:107] op_sel_hi:[1,0]
	v_pk_mul_f32 v[78:79], v[104:105], v[106:107] op_sel_hi:[1,0]
	v_pk_mul_f32 v[80:81], v[102:103], v[106:107] op_sel_hi:[1,0]
	v_pk_mul_f32 v[76:77], v[22:23], v[76:77]
	v_pk_mul_f32 v[74:75], v[24:25], v[74:75]
	v_pk_mul_f32 v[80:81], v[18:19], v[80:81]
	v_pk_mul_f32 v[78:79], v[20:21], v[78:79]
	s_waitcnt vmcnt(6)
	v_pk_add_f32 v[58:59], v[148:149], 1.0 op_sel_hi:[1,0]
	v_pk_add_f32 v[56:57], v[146:147], 1.0 op_sel_hi:[1,0]
	v_pk_add_f32 v[62:63], v[152:153], 1.0 op_sel_hi:[1,0]
	v_pk_add_f32 v[60:61], v[150:151], 1.0 op_sel_hi:[1,0]
	v_pk_fma_f32 v[58:59], v[58:59], v[74:75], v[156:157]
	v_pk_fma_f32 v[56:57], v[56:57], v[76:77], v[154:155]
	v_pk_fma_f32 v[62:63], v[62:63], v[78:79], v[160:161]
	v_pk_fma_f32 v[60:61], v[60:61], v[80:81], v[158:159]
	v_cvt_pk_bf16_f32 v56, v56, v57
	v_cvt_pk_bf16_f32 v57, v58, v59
	v_cvt_pk_bf16_f32 v58, v60, v61
	v_cvt_pk_bf16_f32 v59, v62, v63
	global_store_dwordx4 v[72:73], v[56:59], off offset:-2048 sc1
	s_waitcnt vmcnt(3)
	v_pk_add_f32 v[62:63], v[168:169], 1.0 op_sel_hi:[1,0]
	v_pk_add_f32 v[60:61], v[166:167], 1.0 op_sel_hi:[1,0]
	s_nop 0
	v_pk_add_f32 v[58:59], v[164:165], 1.0 op_sel_hi:[1,0]
	v_pk_add_f32 v[56:57], v[162:163], 1.0 op_sel_hi:[1,0]
	v_pk_fma_f32 v[40:41], v[58:59], v[40:41], v[172:173]
	v_pk_fma_f32 v[36:37], v[56:57], v[36:37], v[170:171]
	v_pk_fma_f32 v[42:43], v[42:43], v[62:63], v[176:177]
	v_pk_fma_f32 v[38:39], v[38:39], v[60:61], v[174:175]
	v_cvt_pk_bf16_f32 v36, v36, v37
	v_cvt_pk_bf16_f32 v37, v40, v41
	v_cvt_pk_bf16_f32 v38, v38, v39
	v_cvt_pk_bf16_f32 v39, v42, v43
	global_store_dwordx4 v[72:73], v[36:39], off offset:-1024 sc1
	s_cbranch_scc1 .LBB0_439

.LBB0_921:
	global_load_dwordx4 v[36:39], v[34:35], off nt
	global_load_dwordx4 v[40:43], v[34:35], off offset:1024 nt
	global_load_dwordx4 v[56:59], v[34:35], off offset:2048 nt
	global_load_dwordx4 v[60:63], v[34:35], off offset:3072 nt
	s_ashr_i32 s6, s98, 12
	s_mul_hi_i32 s7, s6, 0x12000
	s_mul_i32 s6, s6, 0x12000
	s_add_u32 s8, s50, s6
	s_addc_u32 s9, s51, s7
	s_add_u32 s6, s8, 0xc000
	s_addc_u32 s7, s9, 0
	s_add_u32 s8, s8, 0xe000
	s_addc_u32 s9, s9, 0
	global_load_dwordx4 v[64:67], v51, s[6:7] offset:16
	global_load_dwordx4 v[68:71], v51, s[6:7]
	global_load_dwordx4 v[72:75], v51, s[8:9] offset:16
	global_load_dwordx4 v[76:79], v51, s[8:9]
	global_load_dwordx4 v[130:133], v52, s[8:9]
	global_load_dwordx4 v[134:137], v52, s[8:9] offset:16
	global_load_dwordx4 v[138:141], v52, s[6:7]
	global_load_dwordx4 v[142:145], v52, s[6:7] offset:16
	global_load_dwordx4 v[146:149], v53, s[8:9]
	global_load_dwordx4 v[150:153], v53, s[8:9] offset:16
	global_load_dwordx4 v[154:157], v53, s[6:7]
	global_load_dwordx4 v[158:161], v53, s[6:7] offset:16
	global_load_dwordx4 v[162:165], v54, s[8:9]
	global_load_dwordx4 v[166:169], v54, s[8:9] offset:16
	global_load_dwordx4 v[170:173], v54, s[6:7]
	global_load_dwordx4 v[174:177], v54, s[6:7] offset:16
	v_add_co_u32_e32 v80, vcc, s10, v34
	s_add_i32 s98, s98, s101
	s_nop 0
	v_addc_co_u32_e32 v81, vcc, -1, v35, vcc
	s_cmp_lt_i32 s98, s100
	s_waitcnt vmcnt(12)
	v_cvt_f32_f16_sdwa v83, v36 dst_sel:DWORD dst_unused:UNUSED_PAD src0_sel:WORD_1
	v_cvt_f32_f16_sdwa v85, v37 dst_sel:DWORD dst_unused:UNUSED_PAD src0_sel:WORD_1
	v_cvt_f32_f16_sdwa v87, v38 dst_sel:DWORD dst_unused:UNUSED_PAD src0_sel:WORD_1
	v_cvt_f32_f16_sdwa v89, v39 dst_sel:DWORD dst_unused:UNUSED_PAD src0_sel:WORD_1
	v_cvt_f32_f16_e32 v82, v36
	v_cvt_f32_f16_e32 v84, v37
	v_cvt_f32_f16_e32 v86, v38
	v_cvt_f32_f16_e32 v88, v39
	v_cvt_f32_f16_sdwa v91, v40 dst_sel:DWORD dst_unused:UNUSED_PAD src0_sel:WORD_1
	v_cvt_f32_f16_sdwa v93, v41 dst_sel:DWORD dst_unused:UNUSED_PAD src0_sel:WORD_1
	v_cvt_f32_f16_e32 v90, v40
	v_cvt_f32_f16_e32 v92, v41
	v_cvt_f32_f16_e32 v94, v42
	v_cvt_f32_f16_e32 v96, v43
	v_cvt_f32_f16_sdwa v95, v42 dst_sel:DWORD dst_unused:UNUSED_PAD src0_sel:WORD_1
	v_cvt_f32_f16_sdwa v97, v43 dst_sel:DWORD dst_unused:UNUSED_PAD src0_sel:WORD_1
	v_cvt_f32_f16_sdwa v99, v56 dst_sel:DWORD dst_unused:UNUSED_PAD src0_sel:WORD_1
	v_cvt_f32_f16_e32 v98, v56
	v_cvt_f32_f16_sdwa v101, v57 dst_sel:DWORD dst_unused:UNUSED_PAD src0_sel:WORD_1
	v_cvt_f32_f16_e32 v100, v57
	v_cvt_f32_f16_sdwa v103, v58 dst_sel:DWORD dst_unused:UNUSED_PAD src0_sel:WORD_1
	v_cvt_f32_f16_e32 v102, v58
	v_cvt_f32_f16_sdwa v105, v59 dst_sel:DWORD dst_unused:UNUSED_PAD src0_sel:WORD_1
	v_cvt_f32_f16_e32 v104, v59
	v_cvt_f32_f16_sdwa v39, v62 dst_sel:DWORD dst_unused:UNUSED_PAD src0_sel:WORD_1
	v_cvt_f32_f16_e32 v38, v62
	v_cvt_f32_f16_sdwa v43, v63 dst_sel:DWORD dst_unused:UNUSED_PAD src0_sel:WORD_1
	v_cvt_f32_f16_e32 v42, v63
	v_mov_b32_e32 v58, v83
	v_mov_b32_e32 v59, v87
	v_mov_b32_e32 v62, v85
	v_mov_b32_e32 v63, v89
	v_cvt_f32_f16_sdwa v37, v60 dst_sel:DWORD dst_unused:UNUSED_PAD src0_sel:WORD_1
	v_cvt_f32_f16_e32 v36, v60
	v_cvt_f32_f16_sdwa v41, v61 dst_sel:DWORD dst_unused:UNUSED_PAD src0_sel:WORD_1
	v_cvt_f32_f16_e32 v40, v61
	v_mov_b32_e32 v56, v82
	v_mov_b32_e32 v57, v86
	v_mov_b32_e32 v60, v84
	v_mov_b32_e32 v61, v88
	v_mov_b32_e32 v108, v91
	v_mov_b32_e32 v109, v93
	v_pk_mul_f32 v[58:59], v[58:59], v[58:59]
	v_pk_mul_f32 v[62:63], v[62:63], v[62:63]
	v_mov_b32_e32 v106, v90
	v_mov_b32_e32 v107, v92
	v_pk_mul_f32 v[108:109], v[108:109], v[108:109]
	v_pk_fma_f32 v[56:57], v[56:57], v[56:57], v[58:59]
	v_pk_fma_f32 v[58:59], v[60:61], v[60:61], v[62:63]
	v_mul_f32_e32 v110, v94, v94
	v_mul_f32_e32 v112, v96, v96
	v_pk_fma_f32 v[60:61], v[106:107], v[106:107], v[108:109]
	v_pk_add_f32 v[56:57], v[56:57], v[58:59]
	v_pk_mul_f32 v[114:115], v[98:99], v[98:99]
	v_pk_mul_f32 v[116:117], v[100:101], v[100:101]
	v_pk_fma_f32 v[110:111], v[94:95], v[94:95], v[110:111] op_sel_hi:[1,1,0]
	v_pk_fma_f32 v[112:113], v[96:97], v[96:97], v[112:113] op_sel_hi:[1,1,0]
	v_pk_add_f32 v[58:59], v[60:61], v[60:61] op_sel_hi:[0,1]
	v_pk_add_f32 v[56:57], v[56:57], v[56:57] op_sel_hi:[0,1]
	v_mov_b32_e32 v120, v103
	v_mov_b32_e32 v121, v105
	v_mov_b32_e32 v110, v114
	v_mov_b32_e32 v112, v115
	v_mov_b32_e32 v58, v117
	v_mov_b32_e32 v56, v116
	v_mov_b32_e32 v118, v102
	v_mov_b32_e32 v119, v104
	v_pk_mul_f32 v[120:121], v[120:121], v[120:121]
	v_pk_add_f32 v[60:61], v[110:111], v[112:113]
	v_pk_add_f32 v[56:57], v[56:57], v[58:59]
	v_mul_f32_e32 v122, v36, v36
	v_mul_f32_e32 v124, v40, v40
	v_pk_fma_f32 v[62:63], v[118:119], v[118:119], v[120:121]
	v_pk_add_f32 v[56:57], v[60:61], v[56:57]
	v_pk_mul_f32 v[126:127], v[38:39], v[38:39]
	v_pk_mul_f32 v[128:129], v[42:43], v[42:43]
	v_pk_fma_f32 v[122:123], v[36:37], v[36:37], v[122:123] op_sel_hi:[1,1,0]
	v_pk_fma_f32 v[124:125], v[40:41], v[40:41], v[124:125] op_sel_hi:[1,1,0]
	v_pk_add_f32 v[62:63], v[62:63], v[62:63] op_sel_hi:[0,1]
	v_pk_add_f32 v[56:57], v[56:57], v[56:57] op_sel_hi:[0,1]
	v_mov_b32_e32 v122, v126
	v_mov_b32_e32 v124, v127
	v_mov_b32_e32 v62, v128
	v_mov_b32_e32 v56, v129
	v_pk_add_f32 v[106:107], v[122:123], v[124:125]
	v_pk_add_f32 v[56:57], v[62:63], v[56:57]
	v_pk_add_f32 v[78:79], v[78:79], 1.0 op_sel_hi:[1,0]
	v_pk_add_f32 v[56:57], v[106:107], v[56:57]
	v_pk_add_f32 v[76:77], v[76:77], 1.0 op_sel_hi:[1,0]
	v_add_f32_e32 v55, v56, v57
	ds_bpermute_b32 v56, v44, v55
	v_pk_add_f32 v[74:75], v[74:75], 1.0 op_sel_hi:[1,0]
	v_pk_add_f32 v[72:73], v[72:73], 1.0 op_sel_hi:[1,0]
	s_waitcnt lgkmcnt(0)
	v_add_f32_e32 v55, v55, v56
	ds_bpermute_b32 v56, v45, v55
	s_waitcnt lgkmcnt(0)
	v_add_f32_e32 v55, v55, v56
	ds_bpermute_b32 v56, v46, v55
	s_waitcnt lgkmcnt(0)
	v_add_f32_e32 v55, v55, v56
	ds_bpermute_b32 v56, v47, v55
	s_waitcnt lgkmcnt(0)
	v_add_f32_e32 v55, v55, v56
	ds_bpermute_b32 v56, v48, v55
	s_waitcnt lgkmcnt(0)
	v_add_f32_e32 v55, v55, v56
	ds_bpermute_b32 v56, v49, v55
	s_waitcnt lgkmcnt(0)
	v_add_f32_e32 v55, v55, v56
	v_fmamk_f32 v55, v55, 0x3a000000, v50
	v_rsq_f32_e32 v106, v55
	s_nop 0
	v_pk_mul_f32 v[56:57], v[84:85], v[106:107] op_sel_hi:[1,0]
	v_pk_mul_f32 v[58:59], v[82:83], v[106:107] op_sel_hi:[1,0]
	v_pk_mul_f32 v[60:61], v[88:89], v[106:107] op_sel_hi:[1,0]
	v_pk_mul_f32 v[62:63], v[86:87], v[106:107] op_sel_hi:[1,0]
	v_pk_mul_f32 v[58:59], v[6:7], v[58:59]
	v_pk_mul_f32 v[56:57], v[8:9], v[56:57]
	v_pk_mul_f32 v[62:63], v[2:3], v[62:63]
	v_pk_mul_f32 v[60:61], v[4:5], v[60:61]
	v_pk_fma_f32 v[70:71], v[78:79], v[56:57], v[70:71]
	v_pk_fma_f32 v[56:57], v[76:77], v[58:59], v[68:69]
	v_pk_fma_f32 v[60:61], v[74:75], v[60:61], v[66:67]
	v_pk_fma_f32 v[58:59], v[72:73], v[62:63], v[64:65]
	v_cvt_pk_bf16_f32 v56, v56, v57
	v_cvt_pk_bf16_f32 v57, v70, v71
	v_cvt_pk_bf16_f32 v58, v58, v59
	v_cvt_pk_bf16_f32 v59, v60, v61
	global_store_dwordx4 v[80:81], v[56:59], off sc1
	v_pk_mul_f32 v[74:75], v[92:93], v[106:107] op_sel_hi:[1,0]
	v_pk_mul_f32 v[76:77], v[90:91], v[106:107] op_sel_hi:[1,0]
	v_pk_mul_f32 v[78:79], v[96:97], v[106:107] op_sel_hi:[1,0]
	v_pk_mul_f32 v[80:81], v[94:95], v[106:107] op_sel_hi:[1,0]
	v_pk_mul_f32 v[76:77], v[14:15], v[76:77]
	v_pk_mul_f32 v[74:75], v[16:17], v[74:75]
	v_pk_mul_f32 v[80:81], v[10:11], v[80:81]
	v_pk_mul_f32 v[78:79], v[12:13], v[78:79]
	v_add_co_u32_e32 v72, vcc, s11, v34
	v_pk_mul_f32 v[40:41], v[40:41], v[106:107] op_sel_hi:[1,0]
	s_nop 0
	v_addc_co_u32_e32 v73, vcc, -1, v35, vcc
	v_pk_mul_f32 v[36:37], v[36:37], v[106:107] op_sel_hi:[1,0]
	v_pk_mul_f32 v[42:43], v[42:43], v[106:107] op_sel_hi:[1,0]
	v_pk_mul_f32 v[38:39], v[38:39], v[106:107] op_sel_hi:[1,0]
	v_pk_mul_f32 v[36:37], v[30:31], v[36:37]
	v_pk_mul_f32 v[40:41], v[32:33], v[40:41]
	v_pk_mul_f32 v[38:39], v[26:27], v[38:39]
	v_pk_mul_f32 v[42:43], v[28:29], v[42:43]
	v_lshl_add_u64 v[34:35], v[34:35], 0, s[0:1]
	s_waitcnt vmcnt(9)
	v_pk_add_f32 v[58:59], v[132:133], 1.0 op_sel_hi:[1,0]
	v_pk_add_f32 v[56:57], v[130:131], 1.0 op_sel_hi:[1,0]
	v_pk_add_f32 v[62:63], v[136:137], 1.0 op_sel_hi:[1,0]
	v_pk_add_f32 v[60:61], v[134:135], 1.0 op_sel_hi:[1,0]
	v_pk_fma_f32 v[58:59], v[58:59], v[74:75], v[140:141]
	v_pk_fma_f32 v[56:57], v[56:57], v[76:77], v[138:139]
	v_pk_fma_f32 v[62:63], v[62:63], v[78:79], v[144:145]
	v_pk_fma_f32 v[60:61], v[60:61], v[80:81], v[142:143]
	v_cvt_pk_bf16_f32 v56, v56, v57
	v_cvt_pk_bf16_f32 v57, v58, v59
	v_cvt_pk_bf16_f32 v58, v60, v61
	v_cvt_pk_bf16_f32 v59, v62, v63
	global_store_dwordx4 v[72:73], v[56:59], off offset:-3072 sc1
	v_pk_mul_f32 v[74:75], v[100:101], v[106:107] op_sel_hi:[1,0]
	v_pk_mul_f32 v[76:77], v[98:99], v[106:107] op_sel_hi:[1,0]
	v_pk_mul_f32 v[78:79], v[104:105], v[106:107] op_sel_hi:[1,0]
	v_pk_mul_f32 v[80:81], v[102:103], v[106:107] op_sel_hi:[1,0]
	v_pk_mul_f32 v[76:77], v[22:23], v[76:77]
	v_pk_mul_f32 v[74:75], v[24:25], v[74:75]
	v_pk_mul_f32 v[80:81], v[18:19], v[80:81]
	v_pk_mul_f32 v[78:79], v[20:21], v[78:79]
	s_waitcnt vmcnt(6)
	v_pk_add_f32 v[58:59], v[148:149], 1.0 op_sel_hi:[1,0]
	v_pk_add_f32 v[56:57], v[146:147], 1.0 op_sel_hi:[1,0]
	v_pk_add_f32 v[62:63], v[152:153], 1.0 op_sel_hi:[1,0]
	v_pk_add_f32 v[60:61], v[150:151], 1.0 op_sel_hi:[1,0]
	v_pk_fma_f32 v[58:59], v[58:59], v[74:75], v[156:157]
	v_pk_fma_f32 v[56:57], v[56:57], v[76:77], v[154:155]
	v_pk_fma_f32 v[62:63], v[62:63], v[78:79], v[160:161]
	v_pk_fma_f32 v[60:61], v[60:61], v[80:81], v[158:159]
	v_cvt_pk_bf16_f32 v56, v56, v57
	v_cvt_pk_bf16_f32 v57, v58, v59
	v_cvt_pk_bf16_f32 v58, v60, v61
	v_cvt_pk_bf16_f32 v59, v62, v63
	global_store_dwordx4 v[72:73], v[56:59], off offset:-2048 sc1
	s_waitcnt vmcnt(3)
	v_pk_add_f32 v[62:63], v[168:169], 1.0 op_sel_hi:[1,0]
	v_pk_add_f32 v[60:61], v[166:167], 1.0 op_sel_hi:[1,0]
	s_nop 0
	v_pk_add_f32 v[58:59], v[164:165], 1.0 op_sel_hi:[1,0]
	v_pk_add_f32 v[56:57], v[162:163], 1.0 op_sel_hi:[1,0]
	v_pk_fma_f32 v[40:41], v[58:59], v[40:41], v[172:173]
	v_pk_fma_f32 v[36:37], v[56:57], v[36:37], v[170:171]
	v_pk_fma_f32 v[42:43], v[42:43], v[62:63], v[176:177]
	v_pk_fma_f32 v[38:39], v[38:39], v[60:61], v[174:175]
	v_cvt_pk_bf16_f32 v36, v36, v37
	v_cvt_pk_bf16_f32 v37, v40, v41
	v_cvt_pk_bf16_f32 v38, v38, v39
	v_cvt_pk_bf16_f32 v39, v42, v43
	global_store_dwordx4 v[72:73], v[36:39], off offset:-1024 sc1
	s_cbranch_scc1 .LBB0_921
